# hyena row-copy loads batched (8 in flight) and merge transpose loads software-pipelined (8 in flight) instead of one load per vmcnt(0)
# baseline (speedup 1.0000x reference)
.LBB0_1092:
	v_mov_b32_e32 v226, v2
	v_ashrrev_i32_e32 v226, 2, v226
	v_lshlrev_b32_e32 v4, 13, v226
	v_mov_b32_e32 v5, 0
	v_lshl_add_u64 v[4:5], v[0:1], 0, v[4:5]
	global_load_dwordx4 v[194:197], v[4:5], off
	v_add_u32_e32 v227, 256, v2
	v_ashrrev_i32_e32 v227, 2, v227
	v_lshlrev_b32_e32 v4, 13, v227
	v_mov_b32_e32 v5, 0
	v_lshl_add_u64 v[4:5], v[0:1], 0, v[4:5]
	global_load_dwordx4 v[198:201], v[4:5], off
	v_add_u32_e32 v228, 512, v2
	v_ashrrev_i32_e32 v228, 2, v228
	v_lshlrev_b32_e32 v4, 13, v228
	v_mov_b32_e32 v5, 0
	v_lshl_add_u64 v[4:5], v[0:1], 0, v[4:5]
	global_load_dwordx4 v[202:205], v[4:5], off
	v_add_u32_e32 v229, 768, v2
	v_ashrrev_i32_e32 v229, 2, v229
	v_lshlrev_b32_e32 v4, 13, v229
	v_mov_b32_e32 v5, 0
	v_lshl_add_u64 v[4:5], v[0:1], 0, v[4:5]
	global_load_dwordx4 v[206:209], v[4:5], off
	v_add_u32_e32 v230, 1024, v2
	v_ashrrev_i32_e32 v230, 2, v230
	v_lshlrev_b32_e32 v4, 13, v230
	v_mov_b32_e32 v5, 0
	v_lshl_add_u64 v[4:5], v[0:1], 0, v[4:5]
	global_load_dwordx4 v[210:213], v[4:5], off
	v_add_u32_e32 v231, 1280, v2
	v_ashrrev_i32_e32 v231, 2, v231
	v_lshlrev_b32_e32 v4, 13, v231
	v_mov_b32_e32 v5, 0
	v_lshl_add_u64 v[4:5], v[0:1], 0, v[4:5]
	global_load_dwordx4 v[214:217], v[4:5], off
	v_add_u32_e32 v232, 1536, v2
	v_ashrrev_i32_e32 v232, 2, v232
	v_lshlrev_b32_e32 v4, 13, v232
	v_mov_b32_e32 v5, 0
	v_lshl_add_u64 v[4:5], v[0:1], 0, v[4:5]
	global_load_dwordx4 v[218:221], v[4:5], off
	v_add_u32_e32 v233, 1792, v2
	v_ashrrev_i32_e32 v233, 2, v233
	v_lshlrev_b32_e32 v4, 13, v233
	v_mov_b32_e32 v5, 0
	v_lshl_add_u64 v[4:5], v[0:1], 0, v[4:5]
	global_load_dwordx4 v[222:225], v[4:5], off
	s_waitcnt vmcnt(7)
	v_lshl_add_u32 v8, v226, 1, v3
	ds_write_b16 v8, v194
	ds_write_b16_d16_hi v8, v194 offset:2064
	ds_write_b16 v8, v195 offset:4128
	ds_write_b16_d16_hi v8, v195 offset:6192
	ds_write_b16 v8, v196 offset:8256
	ds_write_b16_d16_hi v8, v196 offset:10320
	ds_write_b16 v8, v197 offset:12384
	ds_write_b16_d16_hi v8, v197 offset:14448
	v_add_u32_e32 v226, 2048, v2
	v_ashrrev_i32_e32 v226, 2, v226
	v_lshlrev_b32_e32 v4, 13, v226
	v_mov_b32_e32 v5, 0
	v_lshl_add_u64 v[4:5], v[0:1], 0, v[4:5]
	global_load_dwordx4 v[194:197], v[4:5], off
	s_waitcnt vmcnt(7)
	v_lshl_add_u32 v8, v227, 1, v3
	ds_write_b16 v8, v198
	ds_write_b16_d16_hi v8, v198 offset:2064
	ds_write_b16 v8, v199 offset:4128
	ds_write_b16_d16_hi v8, v199 offset:6192
	ds_write_b16 v8, v200 offset:8256
	ds_write_b16_d16_hi v8, v200 offset:10320
	ds_write_b16 v8, v201 offset:12384
	ds_write_b16_d16_hi v8, v201 offset:14448
	v_add_u32_e32 v227, 2304, v2
	v_ashrrev_i32_e32 v227, 2, v227
	v_lshlrev_b32_e32 v4, 13, v227
	v_mov_b32_e32 v5, 0
	v_lshl_add_u64 v[4:5], v[0:1], 0, v[4:5]
	global_load_dwordx4 v[198:201], v[4:5], off
	s_waitcnt vmcnt(7)
	v_lshl_add_u32 v8, v228, 1, v3
	ds_write_b16 v8, v202
	ds_write_b16_d16_hi v8, v202 offset:2064
	ds_write_b16 v8, v203 offset:4128
	ds_write_b16_d16_hi v8, v203 offset:6192
	ds_write_b16 v8, v204 offset:8256
	ds_write_b16_d16_hi v8, v204 offset:10320
	ds_write_b16 v8, v205 offset:12384
	ds_write_b16_d16_hi v8, v205 offset:14448
	v_add_u32_e32 v228, 2560, v2
	v_ashrrev_i32_e32 v228, 2, v228
	v_lshlrev_b32_e32 v4, 13, v228
	v_mov_b32_e32 v5, 0
	v_lshl_add_u64 v[4:5], v[0:1], 0, v[4:5]
	global_load_dwordx4 v[202:205], v[4:5], off
	s_waitcnt vmcnt(7)
	v_lshl_add_u32 v8, v229, 1, v3
	ds_write_b16 v8, v206
	ds_write_b16_d16_hi v8, v206 offset:2064
	ds_write_b16 v8, v207 offset:4128
	ds_write_b16_d16_hi v8, v207 offset:6192
	ds_write_b16 v8, v208 offset:8256
	ds_write_b16_d16_hi v8, v208 offset:10320
	ds_write_b16 v8, v209 offset:12384
	ds_write_b16_d16_hi v8, v209 offset:14448
	v_add_u32_e32 v229, 2816, v2
	v_ashrrev_i32_e32 v229, 2, v229
	v_lshlrev_b32_e32 v4, 13, v229
	v_mov_b32_e32 v5, 0
	v_lshl_add_u64 v[4:5], v[0:1], 0, v[4:5]
	global_load_dwordx4 v[206:209], v[4:5], off
	s_waitcnt vmcnt(7)
	v_lshl_add_u32 v8, v230, 1, v3
	ds_write_b16 v8, v210
	ds_write_b16_d16_hi v8, v210 offset:2064
	ds_write_b16 v8, v211 offset:4128
	ds_write_b16_d16_hi v8, v211 offset:6192
	ds_write_b16 v8, v212 offset:8256
	ds_write_b16_d16_hi v8, v212 offset:10320
	ds_write_b16 v8, v213 offset:12384
	ds_write_b16_d16_hi v8, v213 offset:14448
	v_add_u32_e32 v230, 3072, v2
	v_ashrrev_i32_e32 v230, 2, v230
	v_lshlrev_b32_e32 v4, 13, v230
	v_mov_b32_e32 v5, 0
	v_lshl_add_u64 v[4:5], v[0:1], 0, v[4:5]
	global_load_dwordx4 v[210:213], v[4:5], off
	s_waitcnt vmcnt(7)
	v_lshl_add_u32 v8, v231, 1, v3
	ds_write_b16 v8, v214
	ds_write_b16_d16_hi v8, v214 offset:2064
	ds_write_b16 v8, v215 offset:4128
	ds_write_b16_d16_hi v8, v215 offset:6192
	ds_write_b16 v8, v216 offset:8256
	ds_write_b16_d16_hi v8, v216 offset:10320
	ds_write_b16 v8, v217 offset:12384
	ds_write_b16_d16_hi v8, v217 offset:14448
	v_add_u32_e32 v231, 3328, v2
	v_ashrrev_i32_e32 v231, 2, v231
	v_lshlrev_b32_e32 v4, 13, v231
	v_mov_b32_e32 v5, 0
	v_lshl_add_u64 v[4:5], v[0:1], 0, v[4:5]
	global_load_dwordx4 v[214:217], v[4:5], off
	s_waitcnt vmcnt(7)
	v_lshl_add_u32 v8, v232, 1, v3
	ds_write_b16 v8, v218
	ds_write_b16_d16_hi v8, v218 offset:2064
	ds_write_b16 v8, v219 offset:4128
	ds_write_b16_d16_hi v8, v219 offset:6192
	ds_write_b16 v8, v220 offset:8256
	ds_write_b16_d16_hi v8, v220 offset:10320
	ds_write_b16 v8, v221 offset:12384
	ds_write_b16_d16_hi v8, v221 offset:14448
	v_add_u32_e32 v232, 3584, v2
	v_ashrrev_i32_e32 v232, 2, v232
	v_lshlrev_b32_e32 v4, 13, v232
	v_mov_b32_e32 v5, 0
	v_lshl_add_u64 v[4:5], v[0:1], 0, v[4:5]
	global_load_dwordx4 v[218:221], v[4:5], off
	s_waitcnt vmcnt(7)
	v_lshl_add_u32 v8, v233, 1, v3
	ds_write_b16 v8, v222
	ds_write_b16_d16_hi v8, v222 offset:2064
	ds_write_b16 v8, v223 offset:4128
	ds_write_b16_d16_hi v8, v223 offset:6192
	ds_write_b16 v8, v224 offset:8256
	ds_write_b16_d16_hi v8, v224 offset:10320
	ds_write_b16 v8, v225 offset:12384
	ds_write_b16_d16_hi v8, v225 offset:14448
	v_add_u32_e32 v233, 3840, v2
	v_ashrrev_i32_e32 v233, 2, v233
	v_lshlrev_b32_e32 v4, 13, v233
	v_mov_b32_e32 v5, 0
	v_lshl_add_u64 v[4:5], v[0:1], 0, v[4:5]
	global_load_dwordx4 v[222:225], v[4:5], off
	s_waitcnt vmcnt(7)
	v_lshl_add_u32 v8, v226, 1, v3
	ds_write_b16 v8, v194
	ds_write_b16_d16_hi v8, v194 offset:2064
	ds_write_b16 v8, v195 offset:4128
	ds_write_b16_d16_hi v8, v195 offset:6192
	ds_write_b16 v8, v196 offset:8256
	ds_write_b16_d16_hi v8, v196 offset:10320
	ds_write_b16 v8, v197 offset:12384
	ds_write_b16_d16_hi v8, v197 offset:14448
	s_waitcnt vmcnt(6)
	v_lshl_add_u32 v8, v227, 1, v3
	ds_write_b16 v8, v198
	ds_write_b16_d16_hi v8, v198 offset:2064
	ds_write_b16 v8, v199 offset:4128
	ds_write_b16_d16_hi v8, v199 offset:6192
	ds_write_b16 v8, v200 offset:8256
	ds_write_b16_d16_hi v8, v200 offset:10320
	ds_write_b16 v8, v201 offset:12384
	ds_write_b16_d16_hi v8, v201 offset:14448
	s_waitcnt vmcnt(5)
	v_lshl_add_u32 v8, v228, 1, v3
	ds_write_b16 v8, v202
	ds_write_b16_d16_hi v8, v202 offset:2064
	ds_write_b16 v8, v203 offset:4128
	ds_write_b16_d16_hi v8, v203 offset:6192
	ds_write_b16 v8, v204 offset:8256
	ds_write_b16_d16_hi v8, v204 offset:10320
	ds_write_b16 v8, v205 offset:12384
	ds_write_b16_d16_hi v8, v205 offset:14448
	s_waitcnt vmcnt(4)
	v_lshl_add_u32 v8, v229, 1, v3
	ds_write_b16 v8, v206
	ds_write_b16_d16_hi v8, v206 offset:2064
	ds_write_b16 v8, v207 offset:4128
	ds_write_b16_d16_hi v8, v207 offset:6192
	ds_write_b16 v8, v208 offset:8256
	ds_write_b16_d16_hi v8, v208 offset:10320
	ds_write_b16 v8, v209 offset:12384
	ds_write_b16_d16_hi v8, v209 offset:14448
	s_waitcnt vmcnt(3)
	v_lshl_add_u32 v8, v230, 1, v3
	ds_write_b16 v8, v210
	ds_write_b16_d16_hi v8, v210 offset:2064
	ds_write_b16 v8, v211 offset:4128
	ds_write_b16_d16_hi v8, v211 offset:6192
	ds_write_b16 v8, v212 offset:8256
	ds_write_b16_d16_hi v8, v212 offset:10320
	ds_write_b16 v8, v213 offset:12384
	ds_write_b16_d16_hi v8, v213 offset:14448
	s_waitcnt vmcnt(2)
	v_lshl_add_u32 v8, v231, 1, v3
	ds_write_b16 v8, v214
	ds_write_b16_d16_hi v8, v214 offset:2064
	ds_write_b16 v8, v215 offset:4128
	ds_write_b16_d16_hi v8, v215 offset:6192
	ds_write_b16 v8, v216 offset:8256
	ds_write_b16_d16_hi v8, v216 offset:10320
	ds_write_b16 v8, v217 offset:12384
	ds_write_b16_d16_hi v8, v217 offset:14448
	s_waitcnt vmcnt(1)
	v_lshl_add_u32 v8, v232, 1, v3
	ds_write_b16 v8, v218
	ds_write_b16_d16_hi v8, v218 offset:2064
	ds_write_b16 v8, v219 offset:4128
	ds_write_b16_d16_hi v8, v219 offset:6192
	ds_write_b16 v8, v220 offset:8256
	ds_write_b16_d16_hi v8, v220 offset:10320
	ds_write_b16 v8, v221 offset:12384
	ds_write_b16_d16_hi v8, v221 offset:14448
	s_waitcnt vmcnt(0)
	v_lshl_add_u32 v8, v233, 1, v3
	ds_write_b16 v8, v222
	ds_write_b16_d16_hi v8, v222 offset:2064
	ds_write_b16 v8, v223 offset:4128
	ds_write_b16_d16_hi v8, v223 offset:6192
	ds_write_b16 v8, v224 offset:8256
	ds_write_b16_d16_hi v8, v224 offset:10320
	ds_write_b16 v8, v225 offset:12384
	ds_write_b16_d16_hi v8, v225 offset:14448
	v_readfirstlane_b32 s8, v167
	s_waitcnt lgkmcnt(0)
	s_mov_b64 s[20:21], exec
	v_readlane_b32 s0, v254, 48
	v_readlane_b32 s1, v254, 49
	s_and_b64 s[0:1], s[20:21], s[0:1]
	s_mov_b64 exec, s[0:1]
	s_cbranch_execz .LBB0_1099
	s_mov_b64 s[0:1], exec
	s_lshr_b32 s8, s8, 4
	s_and_b32 s8, s8, 0xffffff0
	v_mbcnt_lo_u32_b32 v0, s0, 0
	s_add_i32 s11, s8, 0
	v_mbcnt_hi_u32_b32 v0, s1, v0
	s_add_i32 s11, s11, 0x220c0
	v_cmp_eq_u32_e32 vcc, 0, v0
	s_and_saveexec_b64 s[8:9], vcc
	s_bcnt1_i32_b64 s0, s[0:1]
	v_mov_b32_e32 v1, s11
	v_mov_b32_e32 v3, s0
	ds_add_rtn_u32 v1, v1, v3
	s_or_b64 exec, exec, s[8:9]
	s_waitcnt lgkmcnt(0)
	v_readfirstlane_b32 s0, v1
	v_mov_b32_e32 v1, s11
	ds_read_b32 v1, v1
	v_add_u32_e32 v0, s0, v0
	v_bitop3_b32 v0, v0, -4, v0 bitop3:0xc
	s_waitcnt lgkmcnt(0)
	v_add_u32_e32 v1, v0, v1
	v_cmp_gt_i32_e32 vcc, 0, v1
	s_and_b64 exec, exec, vcc
	s_cbranch_execz .LBB0_1099
	s_mov_b64 s[0:1], 0
